# P2: each workgroup runs its mixer-A unit as unit number (blockIdx>>3)%5 among its four mixer-B units (about a fifth of the CUs in A code at any time)
# speedup vs baseline: 1.0138x; 1.0039x over previous
; __global__ void __launch_bounds__(512, 2) fwd_kernel(Args A) {
;     ...
;             for (int u = bx; u < 256 + 1024; u += G) {
;                 if (u < 256) attnA_unit(lds, A, u);
;                 if (u >= 256) {
;                     int ub = u - 256;
;                     if (G == 256) {
;                         const int k = ub >> 8, xcd = bx & 7, j = (bx >> 3) * 4 + k;
;                         ub = (xcd >> 1) * 256 + ((xcd & 1) * 4 + (j >> 5)) * 32 + (j & 31); }
;                     attnB_unit(lds, A, ub, A.kng + l * 64);
;                 }
.LBB0_272:
	s_andn2_b64 vcc, exec, s[4:5]
	s_cbranch_vccnz .LBB0_360
	v_readlane_b32 s4, v254, 44
	v_readlane_b32 s5, v254, 45
	s_andn2_b64 vcc, exec, s[4:5]
	s_cbranch_vccnz .LBB0_328
	v_readlane_b32 s4, v255, 44
	v_readlane_b32 s5, v255, 45
	s_lshl_b32 s60, s4, 6
	s_lshl_b64 s[4:5], s[60:61], 2
	s_add_u32 s4, s56, s4
	s_addc_u32 s5, s57, s5
	v_writelane_b32 v255, s4, 48
	s_mov_b32 s69, s2
	s_mov_b32 s70, s2
	v_writelane_b32 v255, s5, 49
	s_cmpk_eq_i32 s26, 0x100
	s_cbranch_scc0 .LBB0_277
	s_mov_b32 s4, 0
	s_branch .Lp2_decide

; __global__ void __launch_bounds__(512, 2) fwd_kernel(Args A) {
;     ...
;             for (int u = bx; u < 256 + 1024; u += G) {
;                 if (u < 256) attnA_unit(lds, A, u);
;                 if (u >= 256) {
;                     int ub = u - 256;
;                     if (G == 256) {
;                         const int k = ub >> 8, xcd = bx & 7, j = (bx >> 3) * 4 + k;
;                         ub = (xcd >> 1) * 256 + ((xcd & 1) * 4 + (j >> 5)) * 32 + (j & 31); }
;                     attnB_unit(lds, A, ub, A.kng + l * 64);
;                 }
;  }
.LBB0_276:
	s_cmpk_eq_i32 s26, 0x100
	s_cbranch_scc0 .Lp2_orig
	v_readlane_b32 s4, v255, 62
	s_cmpk_lt_i32 s70, 0x100
	s_cbranch_scc0 .Lp2_wasB
	s_or_b32 s4, s4, 0x100
	s_branch .Lp2_decide
.Lp2_wasB:
	s_add_i32 s4, s4, 1
.Lp2_decide:
	v_writelane_b32 v255, s4, 62
	s_and_b32 s5, s4, 0xff
	s_lshr_b32 s6, s2, 3
	s_mul_i32 s7, s6, 0xcd
	s_lshr_b32 s7, s7, 10
	s_mul_i32 s7, s7, 5
	s_sub_i32 s6, s6, s7
	s_bitcmp1_b32 s4, 8
	s_cbranch_scc1 .Lp2_takeB
	s_cmp_eq_u32 s5, s6
	s_cbranch_scc1 .Lp2_takeA
	s_cmp_eq_u32 s5, 4
	s_cbranch_scc1 .Lp2_takeA
.Lp2_takeB:
	s_cmp_ge_u32 s5, 4
	s_cbranch_scc1 .LBB0_328
	s_add_i32 s5, s5, 1
	s_lshl_b32 s5, s5, 8
	s_add_i32 s70, s2, s5
	s_mov_b32 s69, s70
	s_branch .LBB0_277
.Lp2_takeA:
	s_mov_b32 s69, s2
	s_mov_b32 s70, s2
	s_branch .LBB0_277
